# weight-prep part A of the next layer moved into the tail of the output-projection phase (single-tile workgroups)
# speedup vs baseline: 1.0273x; 1.0090x over previous
; #define LAS __attribute__((address_space(3)))
; #define otid() ((wv << 6) | olane())
; __device__ __forceinline__ void convert_weights(LAS unsigned char* lds, KP p, int l, int wv) {
;     unsigned char* ws = p->ws;
;     const int tid_ = otid(); const int lane = tid_ & 63, wid = tid_ >> 6;
;     LAS float* scr = (LAS float*)(lds + wid * 8704);
;     const int gw = blockIdx.x * 8 + wid, NGW = gridDim.x * 8;
;     constexpr int I_IN = 16 * (DIN / 32), I_UQ = 6 * 24, I_UKV = 4 * 32, I_BR = 8 * 32, I_O = 16 * 32, I_F1 = 16 * 128, I_F2 = 64 * 32;
;     constexpr int NIT = I_IN + I_UQ + I_UKV + 3 * I_BR + I_O + I_F1 + I_F2;
;     const int BIG = 1 << 30;
;     for (int it = gw; it < NIT; it += NGW) {
;         int r = it;
;         if (r < I_IN) { tr_item(p->w_in + (size_t)l * DM * DIN, DIN, (bf16_t*)(ws + WS_WIN), DM, 0, NGATE0, NPM - NGATE0, 1, 0, scr, r, lane); continue; } r -= I_IN;
.LBB0_97:
	s_waitcnt lgkmcnt(0)
	v_readlane_b32 s8, v255, 0
	v_readlane_b32 s9, v255, 1
	s_mov_b32 s0, s79
	s_load_dwordx2 s[10:11], s[8:9], 0xd8
	v_mbcnt_lo_u32_b32 v0, -1, 0
	v_mbcnt_hi_u32_b32 v0, -1, v0
	v_readlane_b32 s0, v255, 6
	v_or_b32_e32 v1, s82, v0
	v_ashrrev_i32_e32 v1, 6, v1
	s_mov_b32 s91, s77
	v_add_u32_e32 v18, s0, v1
	s_movk_i32 s0, 0x1460
	s_cmp_lg_u32 s90, 0
	s_cselect_b32 s0, s0, 0
	v_add_u32_e32 v18, s0, v18
	s_movk_i32 s0, 0x2660
	s_lshl_b64 s[12:13], s[90:91], 24
	s_mul_hi_u32 s28, s90, 0x20a0000
	s_mul_i32 s29, s90, 0x20a0000
	v_cmp_gt_i32_e32 vcc, s0, v18
	s_and_saveexec_b64 s[0:1], vcc
	s_cbranch_execz .LBB0_128
	s_movk_i32 s14, 0x2200
	v_bfe_u32 v19, v0, 5, 1
	v_and_b32_e32 v14, 31, v0
	v_bfe_u32 v21, v0, 3, 3
	v_lshlrev_b32_e32 v0, 3, v0
	v_mul_lo_u32 v1, v1, s14
	v_and_b32_e32 v0, 56, v0
	v_add_u32_e32 v4, 0, v1
	v_lshlrev_b32_e32 v1, 2, v14
	v_mul_u32_u24_e32 v2, 0x84, v19
	v_lshlrev_b32_e32 v192, 1, v0
	v_add3_u32 v20, v4, v1, v2
	v_mul_u32_u24_e32 v5, 0x84, v0
	s_waitcnt lgkmcnt(0)
	v_lshl_add_u64 v[0:1], s[10:11], 0, v[192:193]
	s_mov_b64 s[14:15], 0x2700000
	v_lshl_add_u64 v[2:3], v[0:1], 0, s[14:15]
	v_lshlrev_b32_e32 v6, 2, v21
	s_mov_b64 s[14:15], 0x1f00000
	v_add3_u32 v22, v4, v5, v6
	v_lshl_add_u64 v[4:5], v[0:1], 0, s[14:15]
	s_mov_b64 s[14:15], 0x1700000
	v_lshl_add_u64 v[6:7], v[0:1], 0, s[14:15]
	s_mov_b64 s[14:15], 0x1300000
	v_lshl_add_u64 v[8:9], v[0:1], 0, s[14:15]
	s_mov_b64 s[14:15], 0x1200000
	v_lshl_add_u64 v[10:11], v[0:1], 0, s[14:15]
	s_mov_b64 s[14:15], 0x1100000
	v_lshl_add_u64 v[12:13], v[0:1], 0, s[14:15]
	v_readlane_b32 s14, v255, 29
	v_readlane_b32 s15, v255, 30
	v_mov_b32_e32 v15, 0x1c340
	s_lshl_b64 s[2:3], s[90:91], 22
	s_lshl_b64 s[4:5], s[90:91], 23
	s_lshl_b64 s[6:7], s[90:91], 20
	v_or_b32_e32 v23, 8, v21
	v_or_b32_e32 v24, 16, v21
	v_or_b32_e32 v25, 24, v21
	v_lshlrev_b32_e32 v26, 5, v18
	s_lshl_b32 s30, s14, 5
	v_lshl_add_u32 v27, v18, 1, v15
	s_lshl_b32 s31, s14, 1
	s_mov_b64 s[14:15], 0
	v_lshlrev_b32_e32 v14, 2, v14
	v_add_u32_e32 v28, 0x400, v20
	v_add_u32_e32 v29, 0x800, v20
	v_add_u32_e32 v30, 0xc00, v20
	v_add_u32_e32 v31, 0x1000, v20
	v_add_u32_e32 v32, 0x1400, v20
	v_add_u32_e32 v33, 0x1800, v20
	v_add_u32_e32 v34, 0x1c00, v20
	s_branch .LBB0_100

; #define otid() ((wv << 6) | olane())
; __device__ __forceinline__ void convert_weights(LAS unsigned char* lds, KP p, int l, int wv) {
;     ...
;     { const int gt = blockIdx.x * 512 + otid(), NT = gridDim.x * 512; u32x4* z = (u32x4*)((bf16_t*)(ws + WS_WIN) + (size_t)NGATE0 * DM);
;       unsigned z0 = 0u; asm volatile("" : "+v"(z0));
;       for (int i = gt; i < (NPM - NGATE0) * DM / 8; i += NT) z[i] = (u32x4){z0, z0, z0, z0}; }
.LBB0_128:
	s_or_b64 exec, exec, s[0:1]
	s_cmp_lg_u32 s90, 0
	s_cbranch_scc1 .LBB0_146
	v_mbcnt_lo_u32_b32 v0, -1, 0
	v_mbcnt_hi_u32_b32 v0, -1, v0
	v_readlane_b32 s0, v255, 7
	v_or_b32_e32 v0, s67, v0
	s_nop 0
	v_add_u32_e32 v4, s0, v0
	s_movk_i32 s0, 0x3000
	v_mov_b32_e32 v0, v193
	v_cmp_gt_i32_e32 vcc, s0, v4
	s_and_saveexec_b64 s[0:1], vcc
	v_readlane_b32 s6, v255, 23
	v_readlane_b32 s7, v255, 24
	s_cbranch_execz .LBB0_131
	v_ashrrev_i32_e32 v5, 31, v4
	s_waitcnt lgkmcnt(0)
	v_lshl_add_u64 v[6:7], v[4:5], 4, s[10:11]
	s_mov_b64 s[2:3], 0x850000
	v_mov_b32_e32 v1, v0
	v_mov_b32_e32 v2, v0
	v_mov_b32_e32 v3, v0
	v_lshl_add_u64 v[6:7], v[6:7], 0, s[2:3]
	s_mov_b64 s[2:3], 0

; #define LAS __attribute__((address_space(3)))
; __device__ __forceinline__ void bias_gemv(LAS unsigned char* lds, KP p, int l, int wv) {
;     ...
;     __syncthreads();
;     for (int i = tid; i < 2 * 9 * 1024; i += 512) { const int which = i / 9216, r = (i % 9216) >> 10, k = i & 1023; sv[i] = mod[(size_t)r * 6144 + (which ? 3 : 0) * 1024 + k]; }
;     __syncthreads();
;     constexpr int IT1 = (DIN + 63) / 64, IT2 = DFF / 64;
;     for (int it = blockIdx.x; it < IT1 + IT2; it += gridDim.x) {
;         const bool second = it >= IT1; const int n0 = (second ? it - IT1 : it) * 64; const int N = second ? DFF : DIN;
;         const int col = n0 + lane; const bool on = col < N;
;         const float* W = (second ? p->w_ff1 + (size_t)l * DM * DFF : p->w_in + (size_t)l * DM * DIN) + (on ? col : 0);
;         const LAS float* s9 = sv + (second ? 9216 : 0);
.LBB0_158:
	s_or_b64 exec, exec, s[0:1]
	v_readlane_b32 s0, v255, 10
	v_readlane_b32 s1, v255, 11
	s_cmpk_lt_i32 s79, 64
	s_cselect_b64 s[2:3], -1, 0
	s_cmp_lg_u32 s90, 0
	s_cselect_b64 s[0:1], s[2:3], s[0:1]
	s_andn2_b64 vcc, exec, s[0:1]
	s_waitcnt lgkmcnt(0)
	s_barrier
	s_cbranch_vccnz .LBB0_171
	v_and_b32_e32 v1, 63, v4
	s_add_i32 s0, 0, 0x12000
	v_lshl_add_u32 v25, v1, 2, s0
	s_movk_i32 s0, 0x240
	v_ashrrev_i32_e32 v3, 6, v0
	v_cmp_gt_i32_e64 s[2:3], s0, v0
	s_add_u32 s0, s10, 0x3180000
	v_lshlrev_b32_e32 v2, 7, v3
	s_addc_u32 s1, s11, 0
	s_movk_i32 s4, 0x900
	s_add_u32 s6, s10, 0x31d0000
	v_mul_lo_u32 v4, v3, s4
	v_lshl_add_u32 v31, v3, 9, 0
	v_ashrrev_i32_e32 v3, 31, v2
	s_addc_u32 s7, s11, 0
	v_or_b32_e32 v27, 0x78, v2
	v_add_u32_e32 v29, -8, v2
	v_lshlrev_b64 v[2:3], 2, v[2:3]
	v_add_u32_e32 v32, v25, v4
	s_movk_i32 s24, 0x83
	s_cmp_lg_u32 s90, 0
	s_cselect_b32 s24, s24, 0
	s_add_i32 s24, s24, s79
	s_branch .LBB0_161

; #define LAS __attribute__((address_space(3)))
; #define otid() ((wv << 6) | olane())
; __device__ __forceinline__ void convert_weights(LAS unsigned char* lds, KP p, int l, int wv) {
;     unsigned char* ws = p->ws;
;     const int tid_ = otid(); const int lane = tid_ & 63, wid = tid_ >> 6;
;     LAS float* scr = (LAS float*)(lds + wid * 8704);
;     const int gw = blockIdx.x * 8 + wid, NGW = gridDim.x * 8;
;     constexpr int I_IN = 16 * (DIN / 32), I_UQ = 6 * 24, I_UKV = 4 * 32, I_BR = 8 * 32, I_O = 16 * 32, I_F1 = 16 * 128, I_F2 = 64 * 32;
;     constexpr int NIT = I_IN + I_UQ + I_UKV + 3 * I_BR + I_O + I_F1 + I_F2;
;     const int BIG = 1 << 30;
;     for (int it = gw; it < NIT; it += NGW) {
;         int r = it;
;         if (r < I_IN) { tr_item(p->w_in + (size_t)l * DM * DIN, DIN, (bf16_t*)(ws + WS_WIN), DM, 0, NGATE0, NPM - NGATE0, 1, 0, scr, r, lane); continue; } r -= I_IN;
.LBB0_1209:
	s_cmp_eq_u32 s90, 3
	s_cbranch_scc1 .Lp0a_skip
	s_cmp_lt_u32 s79, 32
	s_cbranch_scc1 .Lp0a_skip
	v_readlane_b32 s0, v255, 6
	v_readlane_b32 s1, v255, 7
	v_readlane_b32 s2, v255, 23
	v_readlane_b32 s3, v255, 24
	v_readlane_b32 s4, v255, 25
	v_readlane_b32 s5, v255, 26
	v_readlane_b32 s6, v255, 29
	v_readlane_b32 s7, v255, 30
	s_nop 3
	v_writelane_b32 v255, s34, 47
	v_writelane_b32 v255, s35, 48
	v_writelane_b32 v255, s60, 49
	v_writelane_b32 v255, s66, 50
	v_writelane_b32 v255, s0, 51
	v_writelane_b32 v255, s1, 52
	v_writelane_b32 v255, s2, 53
	v_writelane_b32 v255, s3, 54
	v_writelane_b32 v255, s4, 55
	v_writelane_b32 v255, s5, 56
	v_writelane_b32 v255, s6, 57
	v_writelane_b32 v255, s7, 58
	s_sub_i32 s79, s79, 32
	s_movk_i32 s60, 0xe0
	s_mov_b32 s66, 0x1c000
	s_add_i32 s90, s90, 1
	s_lshl_b32 s0, s79, 3
	s_lshl_b32 s1, s79, 9
	s_mov_b32 s2, 0x1c0000
	s_mov_b32 s3, 0
	s_mov_b32 s4, 0x700000
	s_movk_i32 s6, 0x700
	s_mov_b32 s7, 1
	v_writelane_b32 v255, s0, 6
	v_writelane_b32 v255, s1, 7
	v_writelane_b32 v255, s2, 23
	v_writelane_b32 v255, s3, 24
	v_writelane_b32 v255, s4, 25
	v_writelane_b32 v255, s3, 26
	v_writelane_b32 v255, s6, 29
	v_writelane_b32 v255, s3, 30
.La_top:
	s_waitcnt lgkmcnt(0)
	v_readlane_b32 s8, v255, 0
	v_readlane_b32 s9, v255, 1
	s_mov_b32 s0, s79
	s_load_dwordx2 s[10:11], s[8:9], 0xd8
	v_mbcnt_lo_u32_b32 v0, -1, 0
	v_mbcnt_hi_u32_b32 v0, -1, v0
	v_readlane_b32 s0, v255, 6
	v_or_b32_e32 v1, s82, v0
	v_ashrrev_i32_e32 v1, 6, v1
	s_mov_b32 s91, s77
	v_add_u32_e32 v18, s0, v1
	s_movk_i32 s0, 0x1460
	s_lshl_b64 s[12:13], s[90:91], 24
	s_mul_hi_u32 s28, s90, 0x20a0000
	s_mul_i32 s29, s90, 0x20a0000
	v_cmp_gt_i32_e32 vcc, s0, v18
	s_and_saveexec_b64 s[0:1], vcc
	s_cbranch_execz .La_128
	s_movk_i32 s14, 0x2200
	v_bfe_u32 v19, v0, 5, 1
	v_and_b32_e32 v14, 31, v0
	v_bfe_u32 v21, v0, 3, 3
	v_lshlrev_b32_e32 v0, 3, v0
	v_mul_lo_u32 v1, v1, s14
	v_and_b32_e32 v0, 56, v0
	v_add_u32_e32 v4, 0, v1
	v_lshlrev_b32_e32 v1, 2, v14
	v_mul_u32_u24_e32 v2, 0x84, v19
	v_lshlrev_b32_e32 v192, 1, v0
	v_add3_u32 v20, v4, v1, v2
	v_mul_u32_u24_e32 v5, 0x84, v0
	s_waitcnt lgkmcnt(0)
	v_lshl_add_u64 v[0:1], s[10:11], 0, v[192:193]
	s_mov_b64 s[14:15], 0x2700000
	v_lshl_add_u64 v[2:3], v[0:1], 0, s[14:15]
	v_lshlrev_b32_e32 v6, 2, v21
	s_mov_b64 s[14:15], 0x1f00000
	v_add3_u32 v22, v4, v5, v6
	v_lshl_add_u64 v[4:5], v[0:1], 0, s[14:15]
	s_mov_b64 s[14:15], 0x1700000
	v_lshl_add_u64 v[6:7], v[0:1], 0, s[14:15]
	s_mov_b64 s[14:15], 0x1300000
	v_lshl_add_u64 v[8:9], v[0:1], 0, s[14:15]
	s_mov_b64 s[14:15], 0x1200000
	v_lshl_add_u64 v[10:11], v[0:1], 0, s[14:15]
	s_mov_b64 s[14:15], 0x1100000
	v_lshl_add_u64 v[12:13], v[0:1], 0, s[14:15]
	v_readlane_b32 s14, v255, 29
	v_readlane_b32 s15, v255, 30
	v_mov_b32_e32 v15, 0x1c340
	s_lshl_b64 s[2:3], s[90:91], 22
	s_lshl_b64 s[4:5], s[90:91], 23
	s_lshl_b64 s[6:7], s[90:91], 20
	v_or_b32_e32 v23, 8, v21
	v_or_b32_e32 v24, 16, v21
	v_or_b32_e32 v25, 24, v21
	v_lshlrev_b32_e32 v26, 5, v18
	s_lshl_b32 s30, s14, 5
	v_lshl_add_u32 v27, v18, 1, v15
	s_lshl_b32 s31, s14, 1
	s_mov_b64 s[14:15], 0
	v_lshlrev_b32_e32 v14, 2, v14
	v_add_u32_e32 v28, 0x400, v20
	v_add_u32_e32 v29, 0x800, v20
	v_add_u32_e32 v30, 0xc00, v20
	v_add_u32_e32 v31, 0x1000, v20
	v_add_u32_e32 v32, 0x1400, v20
	v_add_u32_e32 v33, 0x1800, v20
	v_add_u32_e32 v34, 0x1c00, v20
	s_branch .La_100
.La_99:
	s_or_b64 exec, exec, s[16:17]
	v_readlane_b32 s16, v255, 29
	v_add_u32_e32 v26, s30, v26
	v_add_u32_e32 v27, s31, v27
	v_add_u32_e32 v18, s16, v18
	s_movk_i32 s16, 0x145f
	v_cmp_lt_i32_e32 vcc, s16, v18
	s_or_b64 s[14:15], vcc, s[14:15]
	v_readlane_b32 s17, v255, 30
	s_andn2_b64 exec, exec, s[14:15]
	s_cbranch_execz .La_128

; #define LAS __attribute__((address_space(3)))
; __device__ __forceinline__ void bias_gemv(LAS unsigned char* lds, KP p, int l, int wv) {
;     ...
;     __syncthreads();
;     constexpr int IT1 = (DIN + 63) / 64, IT2 = DFF / 64;
;     for (int it = blockIdx.x; it < IT1 + IT2; it += gridDim.x) {
;         const bool second = it >= IT1; const int n0 = (second ? it - IT1 : it) * 64; const int N = second ? DFF : DIN;
;         const int col = n0 + lane; const bool on = col < N;
;         const float* W = (second ? p->w_ff1 + (size_t)l * DM * DFF : p->w_in + (size_t)l * DM * DIN) + (on ? col : 0);
;         const LAS float* s9 = sv + (second ? 9216 : 0);
.La_158:
	s_or_b64 exec, exec, s[0:1]
	s_cmpk_lt_i32 s79, 0x83
	s_cselect_b64 s[0:1], -1, 0
	s_andn2_b64 vcc, exec, s[0:1]
	s_waitcnt lgkmcnt(0)
	s_barrier
	s_cbranch_vccnz .La_171
	v_and_b32_e32 v1, 63, v4
	s_add_i32 s0, 0, 0x12000
	v_lshl_add_u32 v25, v1, 2, s0
	s_movk_i32 s0, 0x240
	v_ashrrev_i32_e32 v3, 6, v0
	v_cmp_gt_i32_e64 s[2:3], s0, v0
	s_add_u32 s0, s10, 0x3180000
	v_lshlrev_b32_e32 v2, 7, v3
	s_addc_u32 s1, s11, 0
	s_movk_i32 s4, 0x900
	s_add_u32 s6, s10, 0x31d0000
	v_mul_lo_u32 v4, v3, s4
	v_lshl_add_u32 v31, v3, 9, 0
	v_ashrrev_i32_e32 v3, 31, v2
	s_addc_u32 s7, s11, 0
	v_or_b32_e32 v27, 0x78, v2
	v_add_u32_e32 v29, -8, v2
	v_lshlrev_b64 v[2:3], 2, v[2:3]
	v_add_u32_e32 v32, v25, v4
	s_mov_b32 s24, s79
	s_branch .La_161
.La_160:
	s_or_b64 exec, exec, s[16:17]
	s_add_i32 s24, s24, s60
	s_cmpk_gt_i32 s24, 0x82
	s_barrier
	s_cbranch_scc1 .La_171

; #define PHASE_BEGIN KP p = (KP)__builtin_amdgcn_kernarg_segment_ptr(); asm volatile("" : "+s"(p)); unsigned char* ws = p->ws; const int G = gridDim.x, c = obid(); (void)G; (void)c; (void)ws;
; __global__ void __launch_bounds__(512) mega(Params p_unused, int ph_lo, int ph_hi) {
;     ...
;         for (int rep = 0; rep < REP7; ++rep) { PHASE_BEGIN
;             pg8::Gemm g{(const bf16_t*)(ws + WS_MIX), (const bf16_t*)(ws + WS_WO4), DM, DM, 4096, 0, 0};
;             pg8::Epi<3> E{nullptr, rep ? 12345 : 0, 0, nullptr, 0, nullptr, p->out, (float*)(ws + WS_XC), (const float*)(ws + WS_MOD) + (size_t)l * 9 * 6144 + 2 * 1024, l == 0 ? p->x : (const float*)p->out, l == 0 ? p->ctx : (const float*)(ws + WS_XC),
;                           (const float*)(ws + WS_VM) + ((size_t)l * 2 + 1) * 9 * DM, (bf16_t*)(ws + WS_H), (float*)(ws + WS_PART), nullptr, nullptr, 0};
;             pg8::StaticOrder S; S.init(Mact, DM, G, c);
;             pg8::gemm_phase(lds, g, S, E, wv); }
;         xcd_barrier(xbar, wv);
.La_171:
	s_branch .La_exit
.La_exit:
	v_readlane_b32 s79, v255, 37
	v_readlane_b32 s60, v255, 49
	v_readlane_b32 s66, v255, 50
	v_readlane_b32 s34, v255, 47
	v_readlane_b32 s35, v255, 48
	v_readlane_b32 s0, v255, 51
	v_readlane_b32 s1, v255, 52
	v_readlane_b32 s2, v255, 53
	v_readlane_b32 s3, v255, 54
	v_readlane_b32 s4, v255, 55
	v_readlane_b32 s5, v255, 56
	v_readlane_b32 s6, v255, 57
	v_readlane_b32 s7, v255, 58
	s_sub_i32 s90, s90, 1
	s_nop 3
	v_writelane_b32 v255, s0, 6
	v_writelane_b32 v255, s1, 7
	v_writelane_b32 v255, s2, 23
	v_writelane_b32 v255, s3, 24
	v_writelane_b32 v255, s4, 25
	v_writelane_b32 v255, s5, 26
	v_writelane_b32 v255, s6, 29
	v_writelane_b32 v255, s7, 30
